# rope / qk-norm phase: the row-invariant q/k-norm gain words loaded once before the row loop instead of sixteen hot-line dword gathers per row
# speedup vs baseline: 1.0052x; 1.0052x over previous
.Lgb3_done:
.LBB0_989:
	s_or_b64 exec, exec, s[2:3]
	v_mov_b32_e32 v0, v214
	v_readlane_b32 s3, v253, 0
	s_waitcnt lgkmcnt(0)
	s_barrier
	s_lshl_b32 s3, s3, 3
	v_readfirstlane_b32 s2, v0
	s_ashr_i32 s2, s2, 6
	s_add_i32 s2, s3, s2
	s_cmpk_gt_i32 s2, 0x23ff
	s_cbranch_scc1 .LBB0_1012
	v_and_b32_e32 v58, 63, v0
	v_lshlrev_b32_e32 v3, 3, v0
	v_bfe_u32 v1, v0, 2, 1
	v_and_b32_e32 v6, 24, v3
	v_mov_b32_e32 v3, s71
	v_mov_b32_e32 v5, s69
	v_cmp_gt_u32_e32 vcc, 48, v58
	v_lshlrev_b32_e32 v4, 6, v1
	v_lshlrev_b32_e32 v176, 8, v1
	v_cndmask_b32_e32 v9, v3, v5, vcc
	v_mov_b32_e32 v3, s70
	v_mov_b32_e32 v5, s68
	v_cmp_eq_u32_e64 s[6:7], 0, v1
	v_xor_b32_e32 v1, 1, v218
	v_cndmask_b32_e32 v8, v3, v5, vcc
	v_cmp_lt_i32_e32 vcc, v1, v219
	v_or_b32_e32 v3, 1, v6
	v_or_b32_e32 v5, 2, v6
	v_cndmask_b32_e32 v1, v218, v1, vcc
	v_lshlrev_b32_e32 v59, 2, v1
	v_xor_b32_e32 v1, 2, v218
	v_cmp_lt_i32_e32 vcc, v1, v219
	v_or_b32_e32 v7, 3, v6
	v_cvt_f32_ubyte0_e32 v3, v3
	v_cndmask_b32_e32 v1, v218, v1, vcc
	v_lshlrev_b32_e32 v60, 2, v1
	v_xor_b32_e32 v1, 4, v218
	v_cmp_lt_i32_e32 vcc, v1, v219
	v_cvt_f32_ubyte0_e32 v5, v5
	v_cvt_f32_ubyte0_e32 v7, v7
	v_cndmask_b32_e32 v1, v218, v1, vcc
	v_lshlrev_b32_e32 v61, 2, v1
	v_cvt_f32_ubyte0_e32 v1, v6
	v_mul_f32_e32 v1, 0xbed49a78, v1
	v_exp_f32_e32 v1, v1
	v_mul_f32_e32 v3, 0xbed49a78, v3
	v_mul_f32_e32 v5, 0xbed49a78, v5
	v_mul_f32_e32 v7, 0xbed49a78, v7
	v_exp_f32_e32 v3, v3
	v_exp_f32_e32 v5, v5
	v_exp_f32_e32 v7, v7
	v_mul_f32_e32 v62, 0.15915494, v1
	v_or_b32_e32 v1, 4, v6
	v_cvt_f32_ubyte0_e32 v1, v1
	v_mul_f32_e32 v1, 0xbed49a78, v1
	v_mul_f32_e32 v63, 0.15915494, v3
	v_mul_f32_e32 v64, 0.15915494, v5
	v_mul_f32_e32 v65, 0.15915494, v7
	v_exp_f32_e32 v1, v1
	v_or_b32_e32 v3, 5, v6
	v_or_b32_e32 v5, 6, v6
	v_or_b32_e32 v7, 7, v6
	v_cvt_f32_ubyte0_e32 v3, v3
	v_cvt_f32_ubyte0_e32 v5, v5
	v_cvt_f32_ubyte0_e32 v7, v7
	v_mul_f32_e32 v3, 0xbed49a78, v3
	v_mul_f32_e32 v5, 0xbed49a78, v5
	v_mul_f32_e32 v7, 0xbed49a78, v7
	s_lshl_b32 s90, s96, 7
	v_exp_f32_e32 v3, v3
	v_exp_f32_e32 v5, v5
	v_exp_f32_e32 v7, v7
	v_lshlrev_b32_e32 v2, 4, v0
	v_lshl_add_u64 v[8:9], s[90:91], 2, v[8:9]
	v_mul_f32_e32 v66, 0.15915494, v1
	v_lshlrev_b32_e32 v1, 5, v0
	v_and_b32_e32 v0, 1, v0
	v_lshl_add_u64 v[8:9], v[8:9], 0, v[176:177]
	v_lshlrev_b32_e32 v176, 2, v6
	v_lshlrev_b32_e32 v0, 4, v0
	s_movk_i32 s3, 0x7c0
	v_readlane_b32 s4, v253, 56
	v_and_b32_e32 v2, 0x380, v2
	v_lshl_add_u64 v[8:9], v[8:9], 0, v[176:177]
	v_and_or_b32 v176, v1, s3, v0
	v_readlane_b32 s5, v253, 57
	v_mul_f32_e32 v67, 0.15915494, v3
	v_mul_f32_e32 v68, 0.15915494, v5
	v_mul_f32_e32 v69, 0.15915494, v7
	v_lshlrev_b32_e32 v70, 3, v58
	v_lshl_add_u64 v[10:11], s[4:5], 0, v[176:177]
	v_lshlrev_b32_e32 v176, 1, v2
	v_lshlrev_b32_e32 v12, 1, v4
	v_lshlrev_b32_e32 v14, 1, v6
	global_load_dword v134, v[8:9], off offset:128
	global_load_dword v135, v[8:9], off offset:4
	global_load_dword v136, v[8:9], off offset:132
	global_load_dword v137, v[8:9], off offset:8
	global_load_dword v138, v[8:9], off offset:136
	global_load_dword v139, v[8:9], off offset:12
	global_load_dword v140, v[8:9], off offset:140
	global_load_dword v141, v[8:9], off offset:16
	global_load_dword v142, v[8:9], off offset:144
	global_load_dword v143, v[8:9], off offset:20
	global_load_dword v144, v[8:9], off offset:148
	global_load_dword v145, v[8:9], off offset:24
	global_load_dword v146, v[8:9], off offset:152
	global_load_dword v147, v[8:9], off offset:28
	global_load_dword v148, v[8:9], off offset:156
	global_load_dword v149, v[8:9], off offset:0
	s_ashr_i32 s15, s2, 31
	s_mov_b32 s14, s2
	s_lshl_b64 s[14:15], s[14:15], 13
	v_readlane_b32 s20, v253, 56
	v_readlane_b32 s21, v253, 57
	s_add_u32 s20, s20, s14
	s_addc_u32 s21, s21, s15
	v_lshl_add_u64 v[116:117], s[20:21], 0, v[176:177]
	v_mov_b32_e32 v119, v177
	v_mov_b32_e32 v118, v12
	v_lshl_add_u64 v[116:117], v[116:117], 0, v[118:119]
	v_mov_b32_e32 v118, v14
	v_lshl_add_u64 v[116:117], v[116:117], 0, v[118:119]
	s_mov_b64 s[22:23], 0x1600
	v_lshl_add_u64 v[120:121], v[116:117], 0, s[22:23]
	s_mov_b64 s[22:23], 0x1000
	v_lshl_add_u64 v[116:117], v[116:117], 0, s[22:23]
	global_load_dwordx4 v[100:103], v[116:117], off offset:1536
	global_load_dwordx4 v[104:107], v[120:121], off offset:64
	v_lshl_add_u64 v[122:123], v[10:11], 0, s[14:15]
	global_load_dwordx4 v[126:129], v[122:123], off
	global_load_dwordx4 v[130:133], v[122:123], off offset:32
	global_load_dwordx4 v[108:111], v[122:123], off offset:2048
	global_load_dwordx4 v[112:115], v[122:123], off offset:2080
	s_waitcnt vmcnt(0)
	s_branch .LBB0_992
.LBB0_991:
	s_waitcnt lgkmcnt(0)
	s_add_i32 s14, s2, s88
	s_cmpk_gt_i32 s14, 0x23ff
	s_cselect_b32 s14, s2, s14
	s_ashr_i32 s15, s14, 31
	s_lshl_b64 s[14:15], s[14:15], 13
	v_readlane_b32 s20, v253, 56
	v_readlane_b32 s21, v253, 57
	s_add_u32 s20, s20, s14
	s_addc_u32 s21, s21, s15
	v_lshl_add_u64 v[116:117], s[20:21], 0, v[176:177]
	v_mov_b32_e32 v119, v177
	v_mov_b32_e32 v118, v12
	v_lshl_add_u64 v[116:117], v[116:117], 0, v[118:119]
	v_mov_b32_e32 v118, v14
	v_lshl_add_u64 v[116:117], v[116:117], 0, v[118:119]
	s_mov_b64 s[22:23], 0x1600
	v_lshl_add_u64 v[120:121], v[116:117], 0, s[22:23]
	s_mov_b64 s[22:23], 0x1000
	v_lshl_add_u64 v[116:117], v[116:117], 0, s[22:23]
	global_load_dwordx4 v[100:103], v[116:117], off offset:1536
	global_load_dwordx4 v[104:107], v[120:121], off offset:64
	v_lshl_add_u64 v[122:123], v[10:11], 0, s[14:15]
	global_load_dwordx4 v[126:129], v[122:123], off
	global_load_dwordx4 v[130:133], v[122:123], off offset:32
	global_load_dwordx4 v[108:111], v[122:123], off offset:2048
	global_load_dwordx4 v[112:115], v[122:123], off offset:2080
	v_add_f32_e32 v13, v15, v71
	v_fmamk_f32 v13, v13, 0x3c000000, v215
	v_mul_f32_e32 v15, 0x4f800000, v13
	v_cmp_gt_f32_e32 vcc, s92, v13
	s_add_i32 s2, s2, s88
	s_cmpk_gt_i32 s2, 0x23ff
	v_cndmask_b32_e32 v13, v13, v15, vcc
	v_sqrt_f32_e32 v15, v13
	s_nop 0
	v_add_u32_e32 v71, -1, v15
	v_fma_f32 v73, -v71, v15, v13
	v_add_u32_e32 v72, 1, v15
	v_cmp_ge_f32_e64 s[4:5], 0, v73
	s_nop 1
	v_cndmask_b32_e64 v71, v15, v71, s[4:5]
	v_fma_f32 v15, -v72, v15, v13
	v_cmp_lt_f32_e64 s[4:5], 0, v15
	s_nop 1
	v_cndmask_b32_e64 v15, v71, v72, s[4:5]
	v_mul_f32_e32 v71, 0x37800000, v15
	v_cndmask_b32_e32 v15, v15, v71, vcc
	v_cmp_class_f32_e32 vcc, v13, v216
	s_nop 1
	v_cndmask_b32_e32 v13, v15, v13, vcc
	v_div_scale_f32 v15, s[4:5], v13, v13, 1.0
	v_rcp_f32_e32 v71, v15
	s_nop 0
	v_fma_f32 v72, -v15, v71, 1.0
	v_fmac_f32_e32 v71, v72, v71
	v_div_scale_f32 v72, vcc, 1.0, v13, 1.0
	v_mul_f32_e32 v73, v72, v71
	v_fma_f32 v74, -v15, v73, v72
	v_fmac_f32_e32 v73, v74, v71
	v_fma_f32 v15, -v15, v73, v72
	v_div_fmas_f32 v15, v15, v71, v73
	v_div_fixup_f32 v72, v15, v13, 1.0
	v_pk_mul_f32 v[18:19], v[72:73], v[18:19] op_sel_hi:[0,1]
	v_pk_mul_f32 v[18:19], v[18:19], v[46:47]
	v_pk_mul_f32 v[16:17], v[72:73], v[16:17] op_sel_hi:[0,1]
	v_pk_mul_f32 v[46:47], v[18:19], v[48:49] op_sel:[1,0] op_sel_hi:[0,1]
	v_pk_mul_f32 v[18:19], v[18:19], v[48:49]
	v_pk_mul_f32 v[48:49], v[16:17], v[50:51]
	v_pk_mul_f32 v[16:17], v[72:73], v[26:27] op_sel_hi:[0,1]
	v_pk_mul_f32 v[2:3], v[72:73], v[2:3] op_sel_hi:[0,1]
	v_pk_mul_f32 v[16:17], v[16:17], v[24:25]
	v_pk_mul_f32 v[2:3], v[2:3], v[34:35]
	v_pk_mul_f32 v[24:25], v[16:17], v[32:33] op_sel:[1,0] op_sel_hi:[0,1]
	v_pk_mul_f32 v[26:27], v[2:3], v[28:29] op_sel:[1,0] op_sel_hi:[0,1]
	v_pk_mul_f32 v[6:7], v[72:73], v[6:7] op_sel_hi:[0,1]
	v_pk_mul_f32 v[4:5], v[72:73], v[4:5] op_sel_hi:[0,1]
	v_pk_mul_f32 v[16:17], v[16:17], v[32:33]
	v_mov_b32_e32 v32, v24
	v_mov_b32_e32 v33, v26
	v_mov_b32_e32 v26, v25
	v_pk_mul_f32 v[2:3], v[2:3], v[28:29]
	v_pk_mul_f32 v[6:7], v[6:7], v[40:41]
	v_pk_mul_f32 v[4:5], v[4:5], v[44:45]
	v_pk_add_f32 v[24:25], v[32:33], v[26:27] neg_lo:[0,1] neg_hi:[0,1]
	v_mov_b32_e32 v26, v16
	v_mov_b32_e32 v27, v2
	v_mov_b32_e32 v2, v17
	v_pk_mul_f32 v[40:41], v[6:7], v[42:43] op_sel:[1,0] op_sel_hi:[0,1]
	v_pk_add_f32 v[16:17], v[26:27], v[2:3]
	v_cvt_pk_bf16_f32 v2, v24, v25
	v_pk_mul_f32 v[24:25], v[4:5], v[30:31] op_sel:[1,0] op_sel_hi:[0,1]
	v_pk_mul_f32 v[6:7], v[6:7], v[42:43]
	v_mov_b32_e32 v26, v40
	v_mov_b32_e32 v27, v24
	v_mov_b32_e32 v24, v41
	v_pk_mul_f32 v[4:5], v[4:5], v[30:31]
	v_pk_add_f32 v[24:25], v[26:27], v[24:25] neg_lo:[0,1] neg_hi:[0,1]
	v_mov_b32_e32 v26, v6
	v_mov_b32_e32 v27, v4
	v_mov_b32_e32 v4, v7
	v_pk_add_f32 v[4:5], v[26:27], v[4:5]
	v_cvt_pk_bf16_f32 v16, v16, v17
	v_cvt_pk_bf16_f32 v17, v4, v5
	v_pk_mul_f32 v[4:5], v[48:49], v[36:37] op_sel:[1,0] op_sel_hi:[0,1]
	v_mov_b32_e32 v6, v46
	v_mov_b32_e32 v7, v4
	v_mov_b32_e32 v4, v47
	v_pk_add_f32 v[4:5], v[6:7], v[4:5] neg_lo:[0,1] neg_hi:[0,1]
	v_pk_mul_f32 v[6:7], v[48:49], v[36:37]
	v_pk_mul_f32 v[22:23], v[72:73], v[22:23] op_sel_hi:[0,1]
	v_pk_mul_f32 v[20:21], v[72:73], v[20:21] op_sel_hi:[0,1]
	v_cvt_pk_bf16_f32 v3, v24, v25
	v_mov_b32_e32 v24, v18
	v_mov_b32_e32 v25, v6
	v_mov_b32_e32 v6, v19
	v_pk_mul_f32 v[22:23], v[22:23], v[52:53]
	v_pk_mul_f32 v[20:21], v[20:21], v[56:57]
	v_pk_add_f32 v[6:7], v[24:25], v[6:7]
	v_pk_mul_f32 v[52:53], v[22:23], v[54:55] op_sel:[1,0] op_sel_hi:[0,1]
	v_cvt_pk_bf16_f32 v18, v6, v7
	v_pk_mul_f32 v[6:7], v[20:21], v[38:39] op_sel:[1,0] op_sel_hi:[0,1]
	v_pk_mul_f32 v[22:23], v[22:23], v[54:55]
	v_mov_b32_e32 v24, v52
	v_mov_b32_e32 v25, v6
	v_mov_b32_e32 v6, v53
	v_pk_mul_f32 v[20:21], v[20:21], v[38:39]
	v_pk_add_f32 v[6:7], v[24:25], v[6:7] neg_lo:[0,1] neg_hi:[0,1]
	v_mov_b32_e32 v24, v22
	v_mov_b32_e32 v25, v20
	v_mov_b32_e32 v20, v23
	v_pk_add_f32 v[20:21], v[24:25], v[20:21]
	v_cvt_pk_bf16_f32 v4, v4, v5
	v_cvt_pk_bf16_f32 v5, v6, v7
	v_cvt_pk_bf16_f32 v19, v20, v21
	global_store_dwordx4 v[0:1], v[2:5], off sc1
	global_store_dwordx4 v[0:1], v[16:19], off offset:64 sc1
	s_cbranch_scc1 .LBB0_1012

.LBB0_996:
	v_readlane_b32 s10, v253, 56
	v_readlane_b32 s11, v253, 57
	s_add_u32 s4, s10, s4
	s_addc_u32 s5, s11, s5
	v_lshl_add_u64 v[0:1], s[4:5], 0, v[176:177]
	v_mov_b32_e32 v13, v177
	v_lshl_add_u64 v[0:1], v[0:1], 0, v[12:13]
	v_mov_b32_e32 v15, v177
	v_lshl_add_u64 v[2:3], v[0:1], 0, v[14:15]
	s_mov_b64 s[4:5], 0x1600
	v_lshl_add_u64 v[0:1], v[2:3], 0, s[4:5]
	v_add_co_u32_e32 v2, vcc, 0x1000, v2
	v_cndmask_b32_e64 v13, v25, v24, s[6:7]
	s_nop 0
	v_addc_co_u32_e32 v3, vcc, 0, v3, vcc
	s_andn2_b64 vcc, exec, s[8:9]
	v_mov_b32_e32 v26, v100
	v_mov_b32_e32 v27, v101
	v_mov_b32_e32 v28, v102
	v_mov_b32_e32 v29, v103
	v_mov_b32_e32 v30, v104
	v_mov_b32_e32 v31, v105
	v_mov_b32_e32 v32, v106
	v_mov_b32_e32 v33, v107
	v_mov_b32_e32 v25, v149
	v_and_b32_e32 v3, 0xffff0000, v26
	v_and_b32_e32 v2, 0xffff0000, v30
	v_lshlrev_b32_e32 v7, 16, v27
	v_and_b32_e32 v5, 0xffff0000, v27
	v_lshlrev_b32_e32 v27, 16, v26
	v_lshlrev_b32_e32 v26, 16, v30
	v_lshlrev_b32_e32 v6, 16, v31
	v_and_b32_e32 v4, 0xffff0000, v31
	v_lshlrev_b32_e32 v19, 16, v28
	v_and_b32_e32 v17, 0xffff0000, v28
	v_lshlrev_b32_e32 v23, 16, v29
	v_and_b32_e32 v21, 0xffff0000, v29
	v_pk_mul_f32 v[28:29], v[2:3], v[2:3]
	v_pk_mul_f32 v[30:31], v[26:27], v[26:27]
	v_lshlrev_b32_e32 v18, 16, v32
	v_and_b32_e32 v16, 0xffff0000, v32
	v_lshlrev_b32_e32 v22, 16, v33
	v_and_b32_e32 v20, 0xffff0000, v33
	v_pk_mul_f32 v[32:33], v[6:7], v[6:7]
	v_add_f32_e32 v24, v29, v28
	v_add_f32_e32 v28, v31, v30
	v_pk_mul_f32 v[34:35], v[4:5], v[4:5]
	v_mov_b32_e32 v38, v18
	v_mov_b32_e32 v39, v16
	v_add_f32_e32 v24, v28, v24
	v_add_f32_e32 v28, v33, v32
	v_mov_b32_e32 v36, v19
	v_mov_b32_e32 v37, v17
	v_pk_mul_f32 v[38:39], v[38:39], v[38:39]
	v_add_f32_e32 v15, v35, v34
	v_add_f32_e32 v24, v24, v28
	v_pk_fma_f32 v[36:37], v[36:37], v[36:37], v[38:39]
	v_mov_b32_e32 v40, v22
	v_mov_b32_e32 v41, v20
	v_add_f32_e32 v15, v24, v15
	v_mov_b32_e32 v38, v23
	v_mov_b32_e32 v39, v21
	v_pk_mul_f32 v[40:41], v[40:41], v[40:41]
	v_add_f32_e32 v15, v15, v36
	v_pk_fma_f32 v[38:39], v[38:39], v[38:39], v[40:41]
	v_add_f32_e32 v15, v15, v37
	v_add_f32_e32 v15, v15, v38
	v_add_f32_e32 v15, v15, v39
	ds_bpermute_b32 v24, v59, v15
	v_cndmask_b32_e64 v30, 0, 1, s[8:9]
	v_mov_b32_e32 v29, 0
	v_mov_b32_e32 v28, 1.0
	v_cmp_ne_u32_e64 s[4:5], 1, v30
	s_waitcnt lgkmcnt(0)
	v_add_f32_e32 v15, v15, v24
	ds_bpermute_b32 v24, v60, v15
	v_mov_b32_e32 v32, 1.0
	v_mov_b32_e32 v33, 0
	s_waitcnt lgkmcnt(0)
	v_add_f32_e32 v15, v15, v24
	v_mov_b32_e32 v24, v134
	ds_bpermute_b32 v71, v61, v15
	s_cbranch_vccnz .LBB0_998
	v_mul_f32_e32 v30, v13, v62
	v_floor_f32_e32 v30, v30
	v_fma_f32 v30, v13, v62, -v30
	v_sin_f32_e32 v33, v30
	v_cos_f32_e32 v32, v30
.LBB0_998:
	v_mov_b32_e32 v35, v135
	v_mov_b32_e32 v34, v136
	s_and_b64 vcc, exec, s[4:5]
	s_cbranch_vccnz .LBB0_1000
	v_mul_f32_e32 v28, v13, v63
	v_floor_f32_e32 v28, v28
	v_fma_f32 v28, v13, v63, -v28
	v_sin_f32_e32 v29, v28
	v_cos_f32_e32 v28, v28
.LBB0_1000:
	v_mov_b32_e32 v41, v137
	v_mov_b32_e32 v40, v138
	v_mov_b32_e32 v31, 0
	v_mov_b32_e32 v30, 1.0
	s_and_b64 vcc, exec, s[4:5]
	v_mov_b32_e32 v42, 1.0
	v_mov_b32_e32 v43, 0
	s_cbranch_vccnz .LBB0_1002
	v_mul_f32_e32 v36, v13, v64
	v_floor_f32_e32 v36, v36
	v_fma_f32 v36, v13, v64, -v36
	v_sin_f32_e32 v43, v36
	v_cos_f32_e32 v42, v36
.LBB0_1002:
	v_mov_b32_e32 v45, v139
	v_mov_b32_e32 v44, v140
	s_and_b64 vcc, exec, s[4:5]
	s_cbranch_vccnz .LBB0_1004
	v_mul_f32_e32 v30, v13, v65
	v_floor_f32_e32 v30, v30
	v_fma_f32 v30, v13, v65, -v30
	v_sin_f32_e32 v31, v30
	v_cos_f32_e32 v30, v30
.LBB0_1004:
	v_mov_b32_e32 v47, v141
	v_mov_b32_e32 v46, v142
	v_mov_b32_e32 v37, 0
	v_mov_b32_e32 v36, 1.0
	s_and_b64 vcc, exec, s[4:5]
	v_mov_b32_e32 v48, 1.0
	v_mov_b32_e32 v49, 0
	s_cbranch_vccnz .LBB0_1006
	v_mul_f32_e32 v38, v13, v66
	v_floor_f32_e32 v38, v38
	v_fma_f32 v38, v13, v66, -v38
	v_sin_f32_e32 v49, v38
	v_cos_f32_e32 v48, v38
.LBB0_1006:
	v_mov_b32_e32 v51, v143
	v_mov_b32_e32 v50, v144
	s_and_b64 vcc, exec, s[4:5]
	s_cbranch_vccnz .LBB0_1008
	v_mul_f32_e32 v36, v13, v67
	v_floor_f32_e32 v36, v36
	v_fma_f32 v36, v13, v67, -v36
	v_sin_f32_e32 v37, v36
	v_cos_f32_e32 v36, v36
.LBB0_1008:
	v_mov_b32_e32 v53, v145
	v_mov_b32_e32 v52, v146
	v_mov_b32_e32 v39, 0
	v_mov_b32_e32 v38, 1.0
	s_and_b64 vcc, exec, s[4:5]
	v_mov_b32_e32 v54, 1.0
	v_mov_b32_e32 v55, 0
	s_cbranch_vccnz .LBB0_1010
	v_mul_f32_e32 v54, v13, v68
	v_floor_f32_e32 v54, v54
	v_fma_f32 v54, v13, v68, -v54
	v_sin_f32_e32 v55, v54
	v_cos_f32_e32 v54, v54
.LBB0_1010:
	v_mov_b32_e32 v57, v147
	v_mov_b32_e32 v56, v148
	s_and_b64 vcc, exec, s[4:5]
	s_cbranch_vccnz .LBB0_991
	v_mul_f32_e32 v38, v13, v69
	v_floor_f32_e32 v38, v38
	v_fma_f32 v13, v13, v69, -v38
	v_sin_f32_e32 v39, v13
	v_cos_f32_e32 v38, v13
	s_branch .LBB0_991
